# v19 with four start offsets (0,3,6,8 tasks) across the workgroups of an XCD instead of two
# baseline (speedup 1.0000x reference)
.LBB0_371:
	s_add_u32 s0, s62, 0x63200000
	s_addc_u32 s1, s63, 0
	s_add_u32 s72, s62, 0x59200000
	s_addc_u32 s73, s63, 0
	v_writelane_b32 v254, s0, 32
	s_cmp_lt_i32 s88, 4
	s_nop 0
	v_writelane_b32 v254, s1, 33
	s_cselect_b64 s[0:1], -1, 0
	s_cmp_gt_i32 s89, 3
	s_cselect_b64 s[2:3], -1, 0
	s_and_b64 s[0:1], s[0:1], s[2:3]
	s_andn2_b64 vcc, exec, s[0:1]
	s_cbranch_vccnz .LBB0_468
	v_writelane_b32 v254, s57, 34
	v_writelane_b32 v254, s56, 35
	v_writelane_b32 v254, s82, 36
	s_cmpk_gt_i32 s87, 0x9ff
	s_nop 0
	v_writelane_b32 v254, s83, 37
	v_writelane_b32 v254, s87, 38
	s_cbranch_scc1 .LBB0_414
	v_and_b32_e32 v1, 32, v0
	v_cmp_eq_u32_e64 s[2:3], 0, v1
	v_lshrrev_b32_e32 v1, 5, v182
	v_lshrrev_b32_e32 v3, 3, v0
	v_and_b32_e32 v3, 2, v3
	v_bfe_u32 v5, v182, 1, 1
	v_lshlrev_b32_e32 v7, 1, v1
	v_lshlrev_b32_e32 v8, 3, v0
	v_bfe_u32 v2, v0, 2, 2
	v_or_b32_e32 v6, v5, v3
	v_and_b32_e32 v8, 8, v8
	v_bitop3_b32 v3, v5, v7, v3 bitop3:0x36
	v_lshlrev_b32_e32 v5, 11, v1
	v_lshl_or_b32 v8, v2, 6, v8
	v_lshl_or_b32 v2, v2, 8, v5
	v_lshl_or_b32 v5, v3, 4, v2
	v_bitop3_b32 v3, v7, v6, 1 bitop3:0x36
	v_lshl_or_b32 v2, v3, 4, v2
	v_lshlrev_b32_e32 v3, 1, v0
	v_lshrrev_b32_e32 v4, 1, v182
	v_and_b32_e32 v3, 8, v3
	v_cmp_gt_u32_e64 s[6:7], 2, v182
	v_readlane_b32 s4, v254, 16
	v_add_u32_e32 v167, v2, v8
	v_lshlrev_b32_e32 v2, 2, v0
	v_and_or_b32 v3, v4, 4, v3
	v_writelane_b32 v254, s6, 39
	s_add_u32 s74, s62, 0x55200000
	v_and_b32_e32 v2, 12, v2
	v_lshrrev_b32_e32 v6, 2, v3
	v_writelane_b32 v254, s7, 40
	s_addc_u32 s75, s63, 0
	s_lshl_b32 s0, s4, 2
	v_and_or_b32 v7, v0, 19, v3
	v_bitop3_b32 v9, v6, v1, v2 bitop3:0x36
	v_lshrrev_b32_e32 v6, 4, v182
	v_readlane_b32 s5, v254, 0
	s_add_i32 s97, s0, 0
	v_lshlrev_b32_e32 v181, 8, v7
	v_and_b32_e32 v7, 15, v0
	v_or_b32_e32 v2, s0, v6
	v_lshlrev_b32_e32 v6, 2, v6
	s_bfe_u32 s0, s5, 0x20006
	v_bitop3_b32 v11, s0, v7, v6 bitop3:0x36
	s_lshl_b32 s0, s4, 10
	v_lshlrev_b32_e32 v4, 3, v1
	s_add_i32 s94, s0, 0
	s_movk_i32 s0, 0x80
	s_movk_i32 s1, 0xc0
	v_and_b32_e32 v165, 31, v0
	v_or_b32_e32 v180, v5, v8
	v_bitop3_b32 v191, v5, 64, v8 bitop3:0x36
	v_bitop3_b32 v193, v5, s0, v8 bitop3:0x36
	v_bitop3_b32 v195, v5, s1, v8 bitop3:0x36
	v_or_b32_e32 v5, 1, v4
	v_cmp_lt_u32_e64 s[12:13], v5, v165
	v_or_b32_e32 v5, 2, v4
	v_cmp_lt_u32_e64 s[14:15], v5, v165
	v_or_b32_e32 v5, 3, v4
	v_cmp_lt_u32_e64 s[16:17], v5, v165
	v_or_b32_e32 v5, 4, v4
	v_cmp_lt_u32_e64 s[18:19], v5, v165
	v_or_b32_e32 v5, 5, v4
	v_cmp_lt_u32_e64 s[20:21], v5, v165
	v_or_b32_e32 v5, 6, v4
	v_cmp_lt_u32_e64 s[22:23], v5, v165
	v_or_b32_e32 v5, 7, v4
	v_cmp_lt_u32_e64 s[24:25], v5, v165
	v_or_b32_e32 v5, 16, v4
	v_cmp_lt_u32_e64 s[26:27], v5, v165
	v_or_b32_e32 v5, 17, v4
	s_add_i32 s97, s97, 0x10000
	v_cmp_lt_u32_e64 s[28:29], v5, v165
	v_or_b32_e32 v5, 18, v4
	v_cmp_lt_u32_e64 s[30:31], v5, v165
	v_or_b32_e32 v5, 19, v4
	s_cmpk_gt_u32 s5, 0x1bf
	v_cmp_lt_u32_e64 s[34:35], v5, v165
	v_or_b32_e32 v5, 20, v4
	s_cselect_b64 s[0:1], -1, 0
	v_cmp_lt_u32_e64 s[36:37], v5, v165
	v_or_b32_e32 v5, 21, v4
	v_writelane_b32 v254, s0, 0
	s_cmp_eq_u32 s4, 7
	v_mov_b32_e32 v3, 0
	v_cmp_lt_u32_e64 s[38:39], v5, v165
	v_or_b32_e32 v5, 22, v4
	v_writelane_b32 v254, s1, 1
	s_cselect_b64 s[82:83], -1, 0
	s_add_i32 s0, s4, -6
	v_lshlrev_b32_e32 v10, 5, v182
	v_lshlrev_b64 v[6:7], 11, v[2:3]
	v_lshlrev_b32_e32 v183, 4, v9
	v_cmp_lt_u32_e64 s[40:41], v5, v165
	v_or_b32_e32 v5, 23, v4
	v_lshlrev_b64 v[8:9], 10, v[2:3]
	v_readlane_b32 s78, v254, 38
	v_writelane_b32 v254, s0, 41
	s_add_i32 s0, s94, 0xc000
	s_mov_b32 s77, 0
	s_waitcnt vmcnt(0)
	v_lshlrev_b32_e32 v164, 3, v11
	v_xor_b32_e32 v184, 32, v183
	v_xor_b32_e32 v185, 64, v183
	v_xor_b32_e32 v186, 0x60, v183
	v_xor_b32_e32 v187, 0x80, v183
	v_xor_b32_e32 v188, 0xa0, v183
	v_xor_b32_e32 v189, 0xc0, v183
	v_xor_b32_e32 v190, 0xe0, v183
	v_cmp_gt_u32_e64 s[6:7], 32, v182
	v_xor_b32_e32 v192, 0x440, v167
	v_xor_b32_e32 v194, 0x480, v167
	v_xor_b32_e32 v196, 0x4c0, v167
	v_cmp_eq_u32_e64 s[8:9], 0, v182
	v_cmp_lt_u32_e64 s[10:11], v4, v165
	v_cmp_lt_u32_e64 s[42:43], v5, v165
	v_add_u32_e32 v197, 0, v181
	v_lshlrev_b32_e32 v166, 2, v1
	s_xor_b32 s95, s78, 15
	s_add_i32 s88, s78, 0xfffffa00
	s_add_i32 s47, s4, -11
	s_add_i32 s92, s4, -7
	v_or_b32_e32 v198, 0xe0, v4
	v_add_u32_e32 v199, s97, v10
	v_lshlrev_b64 v[168:169], 1, v[6:7]
	s_add_i32 s56, s94, 0x2000
	s_add_i32 s57, s94, 0x4000
	s_add_i32 s89, s94, 0x6000
	s_add_i32 s93, s94, 0x8000
	s_add_i32 s68, s94, 0xa000
	v_writelane_b32 v254, s0, 42
	s_add_i32 s0, s94, 0xe000
	s_mov_b32 s5, 0xc3000000
	v_lshlrev_b64 v[170:171], 1, v[8:9]
	s_mov_b32 s80, 0xf149f2ca
	v_mov_b32_e32 v200, 0x80
	v_mov_b32_e32 v201, 0x100
	v_mov_b32_e32 v202, 0x200
	v_mov_b32_e32 v203, 0x400
	v_mov_b32_e32 v204, 0x800
	v_mov_b32_e32 v205, 0x1000
	v_mov_b32_e32 v206, 0x2000
	v_mov_b32_e32 v207, 0x4000
	v_mov_b32_e32 v208, 0x8000
	v_lshlrev_b32_e32 v172, 1, v4
	v_mov_b32_e32 v209, 0xf149f2ca
	v_writelane_b32 v254, s0, 43
	v_writelane_b32 v254, s78, 44
	s_xor_b32 s0, s78, 15
	s_add_i32 s0, s0, s78
	s_nop 0
	v_writelane_b32 v254, s0, 46
	s_lshr_b32 s0, s78, 3
	s_and_b32 s0, s0, 3
	s_mul_i32 s1, s0, 3
	s_cmp_eq_u32 s0, 3
	s_cselect_b32 s1, 8, s1
	s_mul_i32 s1, s1, s96
	s_add_i32 s78, s78, s1
	s_cmpk_lt_i32 s78, 0xa00
	s_cbranch_scc1 .Lp3norot
	v_readlane_b32 s78, v254, 44
	s_nop 1
